# v46: v37 + GEMM MFMA pairs in k-serpentine order (adjacent MFMAs across a pair boundary read the same weight fragment register)
# baseline (speedup 1.0000x reference)
; #define PG8_STAGE(bufoff, gbase, voff) do { _Pragma("unroll") for (int _i = 0; _i < 2; ++_i) \
;         __builtin_amdgcn_global_load_lds((const unsigned*)((const char*)(gbase) + (voff)[_i]), (LAS unsigned*)(lds + (bufoff) + ldsw + _i * 8192), 16, 0, 0); } while (0)
; #define PG8_LDA(dst, b, h) do { _Pragma("unroll") for (int m = 0; m < 4; ++m) _Pragma("unroll") for (int k = 0; k < 2; ++k) dst[m][k] = *(const LAS bf16x8*)(lds + PG8_SA(b, h) + aoff + m * 2048 + k * 1024); } while (0)
; #define PG8_LDB(dst, b, h) do { _Pragma("unroll") for (int n = 0; n < 2; ++n) _Pragma("unroll") for (int k = 0; k < 2; ++k) dst[n][k] = *(const LAS bf16x8*)(lds + PG8_SB(b, h) + boff + n * 2048 + k * 1024); } while (0)
; #define PG8_MMA(ai, bj, At, Bt) do { __builtin_amdgcn_s_setprio(3); _Pragma("unroll") for (int m = 0; m < 4; ++m) _Pragma("unroll") for (int n = 0; n < 2; ++n) _Pragma("unroll") for (int k = 0; k < 2; ++k) \
;         acc[ai][bj][m][n] = __builtin_amdgcn_mfma_f32_16x16x32_bf16(Bt[n][k], At[m][k], acc[ai][bj][m][n], 0, 0, 0); __builtin_amdgcn_s_setprio(0); } while (0)
; #define PG8_WAIT_V(n) asm volatile("s_waitcnt vmcnt(" #n ")" ::: "memory")
; #define PG8_WAIT_L(n) asm volatile("s_waitcnt lgkmcnt(" #n ")" ::: "memory")
; #define PG8_BAR __builtin_amdgcn_s_barrier()
; #define PG8_SCHED __builtin_amdgcn_sched_barrier(0)
; template <class Epi>
; __device__ __forceinline__ void gemm_phase(LAS unsigned char* lds, const Gemm g, const StaticOrder& S, const Epi& E, const int tid) {
;     ...
;             const bool last = (t == nt - 2);
;             const char* a1 = cA + (size_t)(t + 1) * kstep;
;             const char* a2 = last ? nA : cA + (size_t)(t + 2) * kstep; const char* b2 = last ? nB : cB + (size_t)(t + 2) * kstep;
;             const char* a3 = a2 + kstep; const char* b3 = b2 + kstep;
;             PG8_LDB(B0, 0, 0); PG8_LDB(B1, 0, 1); PG8_SCHED; PG8_LDA(At, 0, 0); PG8_STAGE(PG8_SA(1, 1), a1 + hstepA, voffA);
;             PG8_WAIT_V(8); PG8_WAIT_L(0); PG8_BAR; PG8_MMA(0, 0, At, B0); PG8_MMA(0, 1, At, B1); PG8_BAR; PG8_SCHED;
;             PG8_LDA(At, 0, 1); PG8_STAGE(PG8_SB(0, 0), b2, voffB); PG8_STAGE(PG8_SB(0, 1), b2 + hstepB, voffB); PG8_STAGE(PG8_SA(0, 0), a2, voffA);
;             PG8_WAIT_V(8); PG8_WAIT_L(0); PG8_BAR; PG8_MMA(1, 0, At, B0); PG8_MMA(1, 1, At, B1); PG8_BAR; PG8_SCHED;
.LBB0_264:
	s_add_u32 s30, s6, 0x100
	s_addc_u32 s31, s7, 0
	s_add_u32 s4, s20, 0x80
	s_addc_u32 s5, s21, 0
	s_mov_b32 s6, 0
	s_add_i32 s20, s6, 2
	s_add_u32 s21, s4, 0x80
	s_addc_u32 s7, s5, 0
	s_add_i32 s55, 0, 0x10000
	s_cmp_eq_u32 s48, s6
	s_cselect_b32 s7, s79, s7
	s_cselect_b32 s6, s78, s21
	s_cselect_b32 vcc_hi, s81, s31
	s_cselect_b32 vcc_lo, s80, s30
	s_add_i32 s21, 0, 0x14000
	v_add_u32_e32 v152, s55, v169
	v_add_u32_e32 v156, s21, v169
	ds_read_b128 v[140:143], v152
	ds_read_b128 v[144:147], v152 offset:1024
	ds_read_b128 v[148:151], v152 offset:2048
	ds_read_b128 v[152:155], v152 offset:3072
	ds_read_b128 v[172:175], v156
	ds_read_b128 v[180:183], v156 offset:1024
	ds_read_b128 v[184:187], v156 offset:2048
	ds_read_b128 v[194:197], v156 offset:3072
	v_lshl_add_u64 v[156:157], s[4:5], 0, v[138:139]
	s_add_i32 m0, s94, 0xc000
	ds_read_b128 v[198:201], v171
	ds_read_b128 v[202:205], v171 offset:1024
	ds_read_b128 v[206:209], v171 offset:2048
	ds_read_b128 v[210:213], v171 offset:3072
	ds_read_b128 v[214:217], v171 offset:4096
	ds_read_b128 v[218:221], v171 offset:5120
	ds_read_b128 v[222:225], v171 offset:6144
	ds_read_b128 v[226:229], v171 offset:7168
	global_load_lds_dwordx4 v[156:157], off
	v_lshl_add_u64 v[156:157], s[4:5], 0, v[136:137]
	s_add_i32 m0, s94, 0xe000
	s_nop 0
	global_load_lds_dwordx4 v[156:157], off
	s_waitcnt vmcnt(8)
	s_waitcnt lgkmcnt(0)
	s_barrier
	s_setprio 3
	s_waitcnt lgkmcnt(0)
	v_mfma_f32_16x16x32_bf16 v[124:127], v[140:143], v[198:201], 0
	v_mfma_f32_16x16x32_bf16 v[124:127], v[144:147], v[202:205], v[124:127]
	v_mfma_f32_16x16x32_bf16 v[116:119], v[144:147], v[210:213], 0
	v_mfma_f32_16x16x32_bf16 v[116:119], v[140:143], v[206:209], v[116:119]
	v_mfma_f32_16x16x32_bf16 v[100:103], v[140:143], v[214:217], 0
	v_mfma_f32_16x16x32_bf16 v[100:103], v[144:147], v[218:221], v[100:103]
	v_mfma_f32_16x16x32_bf16 v[84:87], v[144:147], v[226:229], 0
	v_mfma_f32_16x16x32_bf16 v[84:87], v[140:143], v[222:225], v[84:87]
	v_mfma_f32_16x16x32_bf16 v[120:123], v[148:151], v[198:201], 0
	v_mfma_f32_16x16x32_bf16 v[120:123], v[152:155], v[202:205], v[120:123]
	v_mfma_f32_16x16x32_bf16 v[108:111], v[152:155], v[210:213], 0
	v_mfma_f32_16x16x32_bf16 v[108:111], v[148:151], v[206:209], v[108:111]
	v_mfma_f32_16x16x32_bf16 v[92:95], v[148:151], v[214:217], 0
	v_mfma_f32_16x16x32_bf16 v[92:95], v[152:155], v[218:221], v[92:95]
	v_mfma_f32_16x16x32_bf16 v[76:79], v[152:155], v[226:229], 0
	v_mfma_f32_16x16x32_bf16 v[76:79], v[148:151], v[222:225], v[76:79]
	s_setprio 0
	s_setprio 3
	v_mfma_f32_16x16x32_bf16 v[112:115], v[172:175], v[198:201], 0
	v_mfma_f32_16x16x32_bf16 v[112:115], v[180:183], v[202:205], v[112:115]
	v_mfma_f32_16x16x32_bf16 v[96:99], v[180:183], v[210:213], 0
	v_mfma_f32_16x16x32_bf16 v[96:99], v[172:175], v[206:209], v[96:99]
	v_mfma_f32_16x16x32_bf16 v[80:83], v[172:175], v[214:217], 0
	v_mfma_f32_16x16x32_bf16 v[80:83], v[180:183], v[218:221], v[80:83]
	v_mfma_f32_16x16x32_bf16 v[68:71], v[180:183], v[226:229], 0
	v_mfma_f32_16x16x32_bf16 v[68:71], v[172:175], v[222:225], v[68:71]
	v_mfma_f32_16x16x32_bf16 v[104:107], v[184:187], v[198:201], 0
	v_mfma_f32_16x16x32_bf16 v[104:107], v[194:197], v[202:205], v[104:107]
	v_mfma_f32_16x16x32_bf16 v[88:91], v[194:197], v[210:213], 0
	v_mfma_f32_16x16x32_bf16 v[88:91], v[184:187], v[206:209], v[88:91]
	v_mfma_f32_16x16x32_bf16 v[72:75], v[184:187], v[214:217], 0
	v_mfma_f32_16x16x32_bf16 v[72:75], v[194:197], v[218:221], v[72:75]
	v_mfma_f32_16x16x32_bf16 v[64:67], v[194:197], v[226:229], 0
	v_mfma_f32_16x16x32_bf16 v[64:67], v[184:187], v[222:225], v[64:67]
	s_setprio 0
	s_barrier
	s_add_i32 s55, s55, s93
	v_lshl_add_u64 v[156:157], vcc, 0, v[130:131]
	s_mov_b32 m0, s55
	ds_read_b128 v[198:201], v171 offset:16384
	ds_read_b128 v[202:205], v171 offset:17408
	ds_read_b128 v[206:209], v171 offset:18432
	ds_read_b128 v[210:213], v171 offset:19456
	ds_read_b128 v[214:217], v171 offset:20480
	ds_read_b128 v[218:221], v171 offset:21504
	ds_read_b128 v[222:225], v171 offset:22528
	ds_read_b128 v[226:229], v171 offset:23552
	global_load_lds_dwordx4 v[156:157], off
	s_add_i32 m0, s55, 0x2000
	v_lshl_add_u64 v[190:191], vcc, 0, v[134:135]
	s_add_u32 vcc_lo, vcc_lo, s91
	s_addc_u32 vcc_hi, vcc_hi, 0
	s_add_i32 s21, s21, s93
	global_load_lds_dwordx4 v[190:191], off
	v_lshl_add_u64 v[240:241], vcc, 0, v[130:131]
	s_mov_b32 m0, s21
	v_lshl_add_u64 v[242:243], vcc, 0, v[134:135]
	global_load_lds_dwordx4 v[240:241], off
	s_add_i32 m0, s21, 0x2000
	v_lshl_add_u64 v[244:245], s[6:7], 0, v[128:129]
	global_load_lds_dwordx4 v[242:243], off
	s_mov_b32 m0, s94
	v_lshl_add_u64 v[246:247], s[6:7], 0, v[132:133]
	global_load_lds_dwordx4 v[244:245], off
	s_mov_b32 m0, s95
	s_nop 0
	global_load_lds_dwordx4 v[246:247], off
	s_waitcnt vmcnt(8)
	s_waitcnt lgkmcnt(0)
	s_barrier
; #define PG8_STAGE(bufoff, gbase, voff) do { _Pragma("unroll") for (int _i = 0; _i < 2; ++_i) \
;         __builtin_amdgcn_global_load_lds((const unsigned*)((const char*)(gbase) + (voff)[_i]), (LAS unsigned*)(lds + (bufoff) + ldsw + _i * 8192), 16, 0, 0); } while (0)
; #define PG8_LDA(dst, b, h) do { _Pragma("unroll") for (int m = 0; m < 4; ++m) _Pragma("unroll") for (int k = 0; k < 2; ++k) dst[m][k] = *(const LAS bf16x8*)(lds + PG8_SA(b, h) + aoff + m * 2048 + k * 1024); } while (0)
; #define PG8_LDB(dst, b, h) do { _Pragma("unroll") for (int n = 0; n < 2; ++n) _Pragma("unroll") for (int k = 0; k < 2; ++k) dst[n][k] = *(const LAS bf16x8*)(lds + PG8_SB(b, h) + boff + n * 2048 + k * 1024); } while (0)
; #define PG8_MMA(ai, bj, At, Bt) do { __builtin_amdgcn_s_setprio(3); _Pragma("unroll") for (int m = 0; m < 4; ++m) _Pragma("unroll") for (int n = 0; n < 2; ++n) _Pragma("unroll") for (int k = 0; k < 2; ++k) \
;         acc[ai][bj][m][n] = __builtin_amdgcn_mfma_f32_16x16x32_bf16(Bt[n][k], At[m][k], acc[ai][bj][m][n], 0, 0, 0); __builtin_amdgcn_s_setprio(0); } while (0)
; #define PG8_WAIT_V(n) asm volatile("s_waitcnt vmcnt(" #n ")" ::: "memory")
; #define PG8_WAIT_L(n) asm volatile("s_waitcnt lgkmcnt(" #n ")" ::: "memory")
; #define PG8_BAR __builtin_amdgcn_s_barrier()
; #define PG8_SCHED __builtin_amdgcn_sched_barrier(0)
; template <class Epi>
; __device__ __forceinline__ void gemm_phase(LAS unsigned char* lds, const Gemm g, const StaticOrder& S, const Epi& E, const int tid) {
;     ...
;             PG8_WAIT_V(8); PG8_WAIT_L(0); PG8_BAR; PG8_MMA(1, 0, At, B0); PG8_MMA(1, 1, At, B1); PG8_BAR; PG8_SCHED;
;             PG8_LDB(B0, 1, 0); PG8_LDB(B1, 1, 1); PG8_SCHED; PG8_LDA(At, 1, 0); PG8_STAGE(PG8_SA(0, 1), a2 + hstepA, voffA);
;             PG8_WAIT_V(8); PG8_WAIT_L(0); PG8_BAR; PG8_MMA(0, 0, At, B0); PG8_MMA(0, 1, At, B1); PG8_BAR; PG8_SCHED;
	s_setprio 3
	s_waitcnt lgkmcnt(0)
	v_mfma_f32_16x16x32_bf16 v[60:63], v[140:143], v[198:201], 0
	v_mfma_f32_16x16x32_bf16 v[60:63], v[144:147], v[202:205], v[60:63]
	v_mfma_f32_16x16x32_bf16 v[48:51], v[144:147], v[210:213], 0
	v_mfma_f32_16x16x32_bf16 v[48:51], v[140:143], v[206:209], v[48:51]
	v_mfma_f32_16x16x32_bf16 v[32:35], v[140:143], v[214:217], 0
	v_mfma_f32_16x16x32_bf16 v[32:35], v[144:147], v[218:221], v[32:35]
	v_mfma_f32_16x16x32_bf16 v[16:19], v[144:147], v[226:229], 0
	v_mfma_f32_16x16x32_bf16 v[16:19], v[140:143], v[222:225], v[16:19]
	v_mfma_f32_16x16x32_bf16 v[56:59], v[148:151], v[198:201], 0
	v_mfma_f32_16x16x32_bf16 v[56:59], v[152:155], v[202:205], v[56:59]
	v_mfma_f32_16x16x32_bf16 v[40:43], v[152:155], v[210:213], 0
	v_mfma_f32_16x16x32_bf16 v[40:43], v[148:151], v[206:209], v[40:43]
	v_mfma_f32_16x16x32_bf16 v[24:27], v[148:151], v[214:217], 0
	v_mfma_f32_16x16x32_bf16 v[24:27], v[152:155], v[218:221], v[24:27]
	v_mfma_f32_16x16x32_bf16 v[8:11], v[152:155], v[226:229], 0
	v_mfma_f32_16x16x32_bf16 v[8:11], v[148:151], v[222:225], v[8:11]
	s_setprio 0
	s_setprio 3
	v_mfma_f32_16x16x32_bf16 v[52:55], v[172:175], v[198:201], 0
	v_mfma_f32_16x16x32_bf16 v[52:55], v[180:183], v[202:205], v[52:55]
	v_mfma_f32_16x16x32_bf16 v[36:39], v[180:183], v[210:213], 0
	v_mfma_f32_16x16x32_bf16 v[36:39], v[172:175], v[206:209], v[36:39]
	v_mfma_f32_16x16x32_bf16 v[20:23], v[172:175], v[214:217], 0
	v_mfma_f32_16x16x32_bf16 v[20:23], v[180:183], v[218:221], v[20:23]
	v_mfma_f32_16x16x32_bf16 v[4:7], v[180:183], v[226:229], 0
	v_mfma_f32_16x16x32_bf16 v[4:7], v[172:175], v[222:225], v[4:7]
	v_mfma_f32_16x16x32_bf16 v[44:47], v[184:187], v[198:201], 0
	v_mfma_f32_16x16x32_bf16 v[44:47], v[194:197], v[202:205], v[44:47]
	v_mfma_f32_16x16x32_bf16 v[28:31], v[194:197], v[210:213], 0
	v_mfma_f32_16x16x32_bf16 v[28:31], v[184:187], v[206:209], v[28:31]
	v_mfma_f32_16x16x32_bf16 v[12:15], v[184:187], v[214:217], 0
	v_mfma_f32_16x16x32_bf16 v[12:15], v[194:197], v[218:221], v[12:15]
	v_mfma_f32_16x16x32_bf16 v[0:3], v[194:197], v[226:229], 0
	v_mfma_f32_16x16x32_bf16 v[0:3], v[184:187], v[222:225], v[0:3]
	s_setprio 0
	s_barrier
	s_add_i32 s21, 0, 0x18000
	s_add_i32 s55, 0, 0x1c000
	v_add_u32_e32 v152, s21, v169
	v_add_u32_e32 v176, s55, v169
	ds_read_b128 v[140:143], v152
	ds_read_b128 v[144:147], v152 offset:1024
	ds_read_b128 v[148:151], v152 offset:2048
	ds_read_b128 v[152:155], v152 offset:3072
	ds_read_b128 v[172:175], v176
	ds_read_b128 v[180:183], v176 offset:1024
	ds_read_b128 v[184:187], v176 offset:2048
	ds_read_b128 v[194:197], v176 offset:3072
	s_add_u32 s6, s6, s26
	s_addc_u32 s7, s7, 0
	s_mov_b32 m0, s96
	v_lshl_add_u64 v[252:253], s[6:7], 0, v[128:129]
	ds_read_b128 v[198:201], v171 offset:32768
	ds_read_b128 v[202:205], v171 offset:33792
	ds_read_b128 v[206:209], v171 offset:34816
	ds_read_b128 v[210:213], v171 offset:35840
	ds_read_b128 v[214:217], v171 offset:36864
	ds_read_b128 v[218:221], v171 offset:37888
	ds_read_b128 v[222:225], v171 offset:38912
	ds_read_b128 v[226:229], v171 offset:39936
	global_load_lds_dwordx4 v[252:253], off
	v_lshl_add_u64 v[252:253], s[6:7], 0, v[132:133]
	s_mov_b32 m0, s97
	s_nop 0
	global_load_lds_dwordx4 v[252:253], off
	s_waitcnt vmcnt(8)
	s_waitcnt lgkmcnt(0)
	s_barrier
	s_setprio 3
	s_waitcnt lgkmcnt(0)
	v_mfma_f32_16x16x32_bf16 v[124:127], v[140:143], v[198:201], v[124:127]
	v_mfma_f32_16x16x32_bf16 v[124:127], v[144:147], v[202:205], v[124:127]
	v_mfma_f32_16x16x32_bf16 v[116:119], v[144:147], v[210:213], v[116:119]
	v_mfma_f32_16x16x32_bf16 v[116:119], v[140:143], v[206:209], v[116:119]
	v_mfma_f32_16x16x32_bf16 v[100:103], v[140:143], v[214:217], v[100:103]
	v_mfma_f32_16x16x32_bf16 v[100:103], v[144:147], v[218:221], v[100:103]
	v_mfma_f32_16x16x32_bf16 v[84:87], v[144:147], v[226:229], v[84:87]
	v_mfma_f32_16x16x32_bf16 v[84:87], v[140:143], v[222:225], v[84:87]
	v_mfma_f32_16x16x32_bf16 v[120:123], v[148:151], v[198:201], v[120:123]
	v_mfma_f32_16x16x32_bf16 v[120:123], v[152:155], v[202:205], v[120:123]
	v_mfma_f32_16x16x32_bf16 v[108:111], v[152:155], v[210:213], v[108:111]
	v_mfma_f32_16x16x32_bf16 v[108:111], v[148:151], v[206:209], v[108:111]
	v_mfma_f32_16x16x32_bf16 v[92:95], v[148:151], v[214:217], v[92:95]
	v_mfma_f32_16x16x32_bf16 v[92:95], v[152:155], v[218:221], v[92:95]
	v_mfma_f32_16x16x32_bf16 v[76:79], v[152:155], v[226:229], v[76:79]
	v_mfma_f32_16x16x32_bf16 v[76:79], v[148:151], v[222:225], v[76:79]
	s_setprio 0
	s_setprio 3
	v_mfma_f32_16x16x32_bf16 v[112:115], v[172:175], v[198:201], v[112:115]
	v_mfma_f32_16x16x32_bf16 v[112:115], v[180:183], v[202:205], v[112:115]
	v_mfma_f32_16x16x32_bf16 v[96:99], v[180:183], v[210:213], v[96:99]
	v_mfma_f32_16x16x32_bf16 v[96:99], v[172:175], v[206:209], v[96:99]
	v_mfma_f32_16x16x32_bf16 v[80:83], v[172:175], v[214:217], v[80:83]
	v_mfma_f32_16x16x32_bf16 v[80:83], v[180:183], v[218:221], v[80:83]
	v_mfma_f32_16x16x32_bf16 v[68:71], v[180:183], v[226:229], v[68:71]
	v_mfma_f32_16x16x32_bf16 v[68:71], v[172:175], v[222:225], v[68:71]
	v_mfma_f32_16x16x32_bf16 v[104:107], v[184:187], v[198:201], v[104:107]
	v_mfma_f32_16x16x32_bf16 v[104:107], v[194:197], v[202:205], v[104:107]
	v_mfma_f32_16x16x32_bf16 v[88:91], v[194:197], v[210:213], v[88:91]
	v_mfma_f32_16x16x32_bf16 v[88:91], v[184:187], v[206:209], v[88:91]
	v_mfma_f32_16x16x32_bf16 v[72:75], v[184:187], v[214:217], v[72:75]
	v_mfma_f32_16x16x32_bf16 v[72:75], v[194:197], v[218:221], v[72:75]
	v_mfma_f32_16x16x32_bf16 v[64:67], v[194:197], v[226:229], v[64:67]
	v_mfma_f32_16x16x32_bf16 v[64:67], v[184:187], v[222:225], v[64:67]
	s_setprio 0
	s_barrier
; #define PG8_STAGE(bufoff, gbase, voff) do { _Pragma("unroll") for (int _i = 0; _i < 2; ++_i) \
;         __builtin_amdgcn_global_load_lds((const unsigned*)((const char*)(gbase) + (voff)[_i]), (LAS unsigned*)(lds + (bufoff) + ldsw + _i * 8192), 16, 0, 0); } while (0)
; #define PG8_LDA(dst, b, h) do { _Pragma("unroll") for (int m = 0; m < 4; ++m) _Pragma("unroll") for (int k = 0; k < 2; ++k) dst[m][k] = *(const LAS bf16x8*)(lds + PG8_SA(b, h) + aoff + m * 2048 + k * 1024); } while (0)
; #define PG8_LDB(dst, b, h) do { _Pragma("unroll") for (int n = 0; n < 2; ++n) _Pragma("unroll") for (int k = 0; k < 2; ++k) dst[n][k] = *(const LAS bf16x8*)(lds + PG8_SB(b, h) + boff + n * 2048 + k * 1024); } while (0)
; #define PG8_MMA(ai, bj, At, Bt) do { __builtin_amdgcn_s_setprio(3); _Pragma("unroll") for (int m = 0; m < 4; ++m) _Pragma("unroll") for (int n = 0; n < 2; ++n) _Pragma("unroll") for (int k = 0; k < 2; ++k) \
;         acc[ai][bj][m][n] = __builtin_amdgcn_mfma_f32_16x16x32_bf16(Bt[n][k], At[m][k], acc[ai][bj][m][n], 0, 0, 0); __builtin_amdgcn_s_setprio(0); } while (0)
; #define PG8_WAIT_V(n) asm volatile("s_waitcnt vmcnt(" #n ")" ::: "memory")
; #define PG8_WAIT_L(n) asm volatile("s_waitcnt lgkmcnt(" #n ")" ::: "memory")
; #define PG8_BAR __builtin_amdgcn_s_barrier()
; #define PG8_SCHED __builtin_amdgcn_sched_barrier(0)
; template <class Epi>
; __device__ __forceinline__ void gemm_phase(LAS unsigned char* lds, const Gemm g, const StaticOrder& S, const Epi& E, const int tid) {
;     ...
;         for (int t = 0; t < nt; t += 2) {
;             const bool last = (t == nt - 2);
;             const char* a1 = cA + (size_t)(t + 1) * kstep;
;             const char* a2 = last ? nA : cA + (size_t)(t + 2) * kstep; const char* b2 = last ? nB : cB + (size_t)(t + 2) * kstep;
;             const char* a3 = a2 + kstep; const char* b3 = b2 + kstep;
;             PG8_LDB(B0, 0, 0); PG8_LDB(B1, 0, 1); PG8_SCHED; PG8_LDA(At, 0, 0); PG8_STAGE(PG8_SA(1, 1), a1 + hstepA, voffA);
;     ...
;             PG8_LDA(At, 1, 1); PG8_STAGE(PG8_SB(1, 0), b3, voffB); PG8_STAGE(PG8_SB(1, 1), b3 + hstepB, voffB); PG8_STAGE(PG8_SA(1, 0), a3, voffA);
;             PG8_WAIT_V(8); PG8_WAIT_L(0); PG8_BAR; PG8_MMA(1, 0, At, B0); PG8_MMA(1, 1, At, B1); PG8_BAR; PG8_SCHED;
	s_add_i32 s6, s21, s93
	v_lshl_add_u64 v[156:157], v[156:157], 0, s[22:23]
	s_mov_b32 m0, s6
	ds_read_b128 v[198:201], v171 offset:49152
	ds_read_b128 v[202:205], v171 offset:50176
	ds_read_b128 v[206:209], v171 offset:51200
	ds_read_b128 v[210:213], v171 offset:52224
	ds_read_b128 v[214:217], v171 offset:53248
	ds_read_b128 v[218:221], v171 offset:54272
	ds_read_b128 v[222:225], v171 offset:55296
	ds_read_b128 v[226:229], v171 offset:56320
	global_load_lds_dwordx4 v[156:157], off
	v_lshl_add_u64 v[156:157], v[190:191], 0, s[22:23]
	s_add_i32 m0, s6, 0x2000
	s_add_i32 s6, s55, s93
	global_load_lds_dwordx4 v[156:157], off
	v_lshl_add_u64 v[156:157], v[240:241], 0, s[22:23]
	s_mov_b32 m0, s6
	s_nop 0
	global_load_lds_dwordx4 v[156:157], off
	v_lshl_add_u64 v[156:157], v[242:243], 0, s[22:23]
	s_add_i32 m0, s6, 0x2000
	s_nop 0
	global_load_lds_dwordx4 v[156:157], off
	v_lshl_add_u64 v[156:157], v[244:245], 0, s[22:23]
	s_mov_b32 m0, s98
	s_nop 0
	global_load_lds_dwordx4 v[156:157], off
	v_lshl_add_u64 v[156:157], v[246:247], 0, s[22:23]
	s_mov_b32 m0, s99
	s_nop 0
	global_load_lds_dwordx4 v[156:157], off
	s_waitcnt vmcnt(8)
	s_waitcnt lgkmcnt(0)
	s_barrier
	s_setprio 3
	s_waitcnt lgkmcnt(0)
	v_mfma_f32_16x16x32_bf16 v[60:63], v[140:143], v[198:201], v[60:63]
	v_mfma_f32_16x16x32_bf16 v[60:63], v[144:147], v[202:205], v[60:63]
	v_mfma_f32_16x16x32_bf16 v[48:51], v[144:147], v[210:213], v[48:51]
	v_mfma_f32_16x16x32_bf16 v[48:51], v[140:143], v[206:209], v[48:51]
	v_mfma_f32_16x16x32_bf16 v[32:35], v[140:143], v[214:217], v[32:35]
	v_mfma_f32_16x16x32_bf16 v[32:35], v[144:147], v[218:221], v[32:35]
	v_mfma_f32_16x16x32_bf16 v[16:19], v[144:147], v[226:229], v[16:19]
	v_mfma_f32_16x16x32_bf16 v[16:19], v[140:143], v[222:225], v[16:19]
	v_mfma_f32_16x16x32_bf16 v[56:59], v[148:151], v[198:201], v[56:59]
	v_mfma_f32_16x16x32_bf16 v[56:59], v[152:155], v[202:205], v[56:59]
	v_mfma_f32_16x16x32_bf16 v[40:43], v[152:155], v[210:213], v[40:43]
	v_mfma_f32_16x16x32_bf16 v[40:43], v[148:151], v[206:209], v[40:43]
	v_mfma_f32_16x16x32_bf16 v[24:27], v[148:151], v[214:217], v[24:27]
	v_mfma_f32_16x16x32_bf16 v[24:27], v[152:155], v[218:221], v[24:27]
	v_mfma_f32_16x16x32_bf16 v[8:11], v[152:155], v[226:229], v[8:11]
	v_mfma_f32_16x16x32_bf16 v[8:11], v[148:151], v[222:225], v[8:11]
	s_setprio 0
	s_setprio 3
	v_mfma_f32_16x16x32_bf16 v[52:55], v[172:175], v[198:201], v[52:55]
	v_mfma_f32_16x16x32_bf16 v[52:55], v[180:183], v[202:205], v[52:55]
	v_mfma_f32_16x16x32_bf16 v[36:39], v[180:183], v[210:213], v[36:39]
	v_mfma_f32_16x16x32_bf16 v[36:39], v[172:175], v[206:209], v[36:39]
	v_mfma_f32_16x16x32_bf16 v[20:23], v[172:175], v[214:217], v[20:23]
	v_mfma_f32_16x16x32_bf16 v[20:23], v[180:183], v[218:221], v[20:23]
	v_mfma_f32_16x16x32_bf16 v[4:7], v[180:183], v[226:229], v[4:7]
	v_mfma_f32_16x16x32_bf16 v[4:7], v[172:175], v[222:225], v[4:7]
	v_mfma_f32_16x16x32_bf16 v[44:47], v[184:187], v[198:201], v[44:47]
	v_mfma_f32_16x16x32_bf16 v[44:47], v[194:197], v[202:205], v[44:47]
	v_mfma_f32_16x16x32_bf16 v[28:31], v[194:197], v[210:213], v[28:31]
	v_mfma_f32_16x16x32_bf16 v[28:31], v[184:187], v[206:209], v[28:31]
	v_mfma_f32_16x16x32_bf16 v[12:15], v[184:187], v[214:217], v[12:15]
	v_mfma_f32_16x16x32_bf16 v[12:15], v[194:197], v[218:221], v[12:15]
	v_mfma_f32_16x16x32_bf16 v[0:3], v[194:197], v[226:229], v[0:3]
	v_mfma_f32_16x16x32_bf16 v[0:3], v[184:187], v[222:225], v[0:3]
	s_setprio 0
	s_barrier
	s_add_u32 s30, s30, 0x100
	s_addc_u32 s31, s31, 0
	s_add_u32 s4, s4, 0x100
	s_addc_u32 s5, s5, 0
	s_cmp_ge_u32 s20, s89
	s_mov_b32 s6, s20
	s_cbranch_scc1 .Lpg_kloop_done
.LBB0_265:
	s_add_i32 s20, s6, 2
	s_add_u32 s21, s4, 0x80
	s_addc_u32 s7, s5, 0
	s_add_i32 s55, 0, 0x10000
	s_cmp_eq_u32 s48, s6
	s_cselect_b32 s7, s79, s7
	s_cselect_b32 s6, s78, s21
	s_cselect_b32 vcc_hi, s81, s31
	s_cselect_b32 vcc_lo, s80, s30
	s_add_i32 s21, 0, 0x14000
	v_add_u32_e32 v152, s55, v169
	v_add_u32_e32 v156, s21, v169
	ds_read_b128 v[140:143], v152
	ds_read_b128 v[144:147], v152 offset:1024
	ds_read_b128 v[148:151], v152 offset:2048
	ds_read_b128 v[152:155], v152 offset:3072
	ds_read_b128 v[172:175], v156
	ds_read_b128 v[180:183], v156 offset:1024
	ds_read_b128 v[184:187], v156 offset:2048
	ds_read_b128 v[194:197], v156 offset:3072
	v_lshl_add_u64 v[156:157], s[4:5], 0, v[138:139]
	s_add_i32 m0, s94, 0xc000
	ds_read_b128 v[198:201], v171
	ds_read_b128 v[202:205], v171 offset:1024
	ds_read_b128 v[206:209], v171 offset:2048
	ds_read_b128 v[210:213], v171 offset:3072
	ds_read_b128 v[214:217], v171 offset:4096
	ds_read_b128 v[218:221], v171 offset:5120
	ds_read_b128 v[222:225], v171 offset:6144
	ds_read_b128 v[226:229], v171 offset:7168
	global_load_lds_dwordx4 v[156:157], off
	v_lshl_add_u64 v[156:157], s[4:5], 0, v[136:137]
	s_add_i32 m0, s94, 0xe000
	s_nop 0
	global_load_lds_dwordx4 v[156:157], off
	s_waitcnt vmcnt(8)
	s_waitcnt lgkmcnt(0)
	s_barrier
; #define PG8_STAGE(bufoff, gbase, voff) do { _Pragma("unroll") for (int _i = 0; _i < 2; ++_i) \
;         __builtin_amdgcn_global_load_lds((const unsigned*)((const char*)(gbase) + (voff)[_i]), (LAS unsigned*)(lds + (bufoff) + ldsw + _i * 8192), 16, 0, 0); } while (0)
; #define PG8_LDA(dst, b, h) do { _Pragma("unroll") for (int m = 0; m < 4; ++m) _Pragma("unroll") for (int k = 0; k < 2; ++k) dst[m][k] = *(const LAS bf16x8*)(lds + PG8_SA(b, h) + aoff + m * 2048 + k * 1024); } while (0)
; #define PG8_MMA(ai, bj, At, Bt) do { __builtin_amdgcn_s_setprio(3); _Pragma("unroll") for (int m = 0; m < 4; ++m) _Pragma("unroll") for (int n = 0; n < 2; ++n) _Pragma("unroll") for (int k = 0; k < 2; ++k) \
;         acc[ai][bj][m][n] = __builtin_amdgcn_mfma_f32_16x16x32_bf16(Bt[n][k], At[m][k], acc[ai][bj][m][n], 0, 0, 0); __builtin_amdgcn_s_setprio(0); } while (0)
; #define PG8_WAIT_V(n) asm volatile("s_waitcnt vmcnt(" #n ")" ::: "memory")
; #define PG8_WAIT_L(n) asm volatile("s_waitcnt lgkmcnt(" #n ")" ::: "memory")
; #define PG8_BAR __builtin_amdgcn_s_barrier()
; #define PG8_SCHED __builtin_amdgcn_sched_barrier(0)
; template <class Epi>
; __device__ __forceinline__ void gemm_phase(LAS unsigned char* lds, const Gemm g, const StaticOrder& S, const Epi& E, const int tid) {
;     ...
;             PG8_WAIT_V(8); PG8_WAIT_L(0); PG8_BAR; PG8_MMA(0, 0, At, B0); PG8_MMA(0, 1, At, B1); PG8_BAR; PG8_SCHED;
;             PG8_LDA(At, 0, 1); PG8_STAGE(PG8_SB(0, 0), b2, voffB); PG8_STAGE(PG8_SB(0, 1), b2 + hstepB, voffB); PG8_STAGE(PG8_SA(0, 0), a2, voffA);
;             PG8_WAIT_V(8); PG8_WAIT_L(0); PG8_BAR; PG8_MMA(1, 0, At, B0); PG8_MMA(1, 1, At, B1); PG8_BAR; PG8_SCHED;
	s_setprio 3
	s_waitcnt lgkmcnt(0)
	v_mfma_f32_16x16x32_bf16 v[124:127], v[140:143], v[198:201], v[124:127]
	v_mfma_f32_16x16x32_bf16 v[124:127], v[144:147], v[202:205], v[124:127]
	v_mfma_f32_16x16x32_bf16 v[116:119], v[144:147], v[210:213], v[116:119]
	v_mfma_f32_16x16x32_bf16 v[116:119], v[140:143], v[206:209], v[116:119]
	v_mfma_f32_16x16x32_bf16 v[100:103], v[140:143], v[214:217], v[100:103]
	v_mfma_f32_16x16x32_bf16 v[100:103], v[144:147], v[218:221], v[100:103]
	v_mfma_f32_16x16x32_bf16 v[84:87], v[144:147], v[226:229], v[84:87]
	v_mfma_f32_16x16x32_bf16 v[84:87], v[140:143], v[222:225], v[84:87]
	v_mfma_f32_16x16x32_bf16 v[120:123], v[148:151], v[198:201], v[120:123]
	v_mfma_f32_16x16x32_bf16 v[120:123], v[152:155], v[202:205], v[120:123]
	v_mfma_f32_16x16x32_bf16 v[108:111], v[152:155], v[210:213], v[108:111]
	v_mfma_f32_16x16x32_bf16 v[108:111], v[148:151], v[206:209], v[108:111]
	v_mfma_f32_16x16x32_bf16 v[92:95], v[148:151], v[214:217], v[92:95]
	v_mfma_f32_16x16x32_bf16 v[92:95], v[152:155], v[218:221], v[92:95]
	v_mfma_f32_16x16x32_bf16 v[76:79], v[152:155], v[226:229], v[76:79]
	v_mfma_f32_16x16x32_bf16 v[76:79], v[148:151], v[222:225], v[76:79]
	s_setprio 0
	s_setprio 3
	v_mfma_f32_16x16x32_bf16 v[112:115], v[172:175], v[198:201], v[112:115]
	v_mfma_f32_16x16x32_bf16 v[112:115], v[180:183], v[202:205], v[112:115]
	v_mfma_f32_16x16x32_bf16 v[96:99], v[180:183], v[210:213], v[96:99]
	v_mfma_f32_16x16x32_bf16 v[96:99], v[172:175], v[206:209], v[96:99]
	v_mfma_f32_16x16x32_bf16 v[80:83], v[172:175], v[214:217], v[80:83]
	v_mfma_f32_16x16x32_bf16 v[80:83], v[180:183], v[218:221], v[80:83]
	v_mfma_f32_16x16x32_bf16 v[68:71], v[180:183], v[226:229], v[68:71]
	v_mfma_f32_16x16x32_bf16 v[68:71], v[172:175], v[222:225], v[68:71]
	v_mfma_f32_16x16x32_bf16 v[104:107], v[184:187], v[198:201], v[104:107]
	v_mfma_f32_16x16x32_bf16 v[104:107], v[194:197], v[202:205], v[104:107]
	v_mfma_f32_16x16x32_bf16 v[88:91], v[194:197], v[210:213], v[88:91]
	v_mfma_f32_16x16x32_bf16 v[88:91], v[184:187], v[206:209], v[88:91]
	v_mfma_f32_16x16x32_bf16 v[72:75], v[184:187], v[214:217], v[72:75]
	v_mfma_f32_16x16x32_bf16 v[72:75], v[194:197], v[218:221], v[72:75]
	v_mfma_f32_16x16x32_bf16 v[64:67], v[194:197], v[226:229], v[64:67]
	v_mfma_f32_16x16x32_bf16 v[64:67], v[184:187], v[222:225], v[64:67]
	s_setprio 0
	s_barrier
	s_add_i32 s55, s55, s93
	v_lshl_add_u64 v[156:157], vcc, 0, v[130:131]
	s_mov_b32 m0, s55
	ds_read_b128 v[198:201], v171 offset:16384
	ds_read_b128 v[202:205], v171 offset:17408
	ds_read_b128 v[206:209], v171 offset:18432
	ds_read_b128 v[210:213], v171 offset:19456
	ds_read_b128 v[214:217], v171 offset:20480
	ds_read_b128 v[218:221], v171 offset:21504
	ds_read_b128 v[222:225], v171 offset:22528
	ds_read_b128 v[226:229], v171 offset:23552
	global_load_lds_dwordx4 v[156:157], off
	s_add_i32 m0, s55, 0x2000
	v_lshl_add_u64 v[190:191], vcc, 0, v[134:135]
	s_add_u32 vcc_lo, vcc_lo, s91
	s_addc_u32 vcc_hi, vcc_hi, 0
	s_add_i32 s21, s21, s93
	global_load_lds_dwordx4 v[190:191], off
	v_lshl_add_u64 v[240:241], vcc, 0, v[130:131]
	s_mov_b32 m0, s21
	v_lshl_add_u64 v[242:243], vcc, 0, v[134:135]
	global_load_lds_dwordx4 v[240:241], off
	s_add_i32 m0, s21, 0x2000
	v_lshl_add_u64 v[244:245], s[6:7], 0, v[128:129]
	global_load_lds_dwordx4 v[242:243], off
	s_mov_b32 m0, s94
	v_lshl_add_u64 v[246:247], s[6:7], 0, v[132:133]
	global_load_lds_dwordx4 v[244:245], off
	s_mov_b32 m0, s95
	s_nop 0
	global_load_lds_dwordx4 v[246:247], off
	s_waitcnt vmcnt(8)
	s_waitcnt lgkmcnt(0)
	s_barrier
	s_setprio 3
	s_waitcnt lgkmcnt(0)
	v_mfma_f32_16x16x32_bf16 v[60:63], v[140:143], v[198:201], v[60:63]
	v_mfma_f32_16x16x32_bf16 v[60:63], v[144:147], v[202:205], v[60:63]
	v_mfma_f32_16x16x32_bf16 v[48:51], v[144:147], v[210:213], v[48:51]
	v_mfma_f32_16x16x32_bf16 v[48:51], v[140:143], v[206:209], v[48:51]
	v_mfma_f32_16x16x32_bf16 v[32:35], v[140:143], v[214:217], v[32:35]
	v_mfma_f32_16x16x32_bf16 v[32:35], v[144:147], v[218:221], v[32:35]
	v_mfma_f32_16x16x32_bf16 v[16:19], v[144:147], v[226:229], v[16:19]
	v_mfma_f32_16x16x32_bf16 v[16:19], v[140:143], v[222:225], v[16:19]
	v_mfma_f32_16x16x32_bf16 v[56:59], v[148:151], v[198:201], v[56:59]
	v_mfma_f32_16x16x32_bf16 v[56:59], v[152:155], v[202:205], v[56:59]
	v_mfma_f32_16x16x32_bf16 v[40:43], v[152:155], v[210:213], v[40:43]
	v_mfma_f32_16x16x32_bf16 v[40:43], v[148:151], v[206:209], v[40:43]
	v_mfma_f32_16x16x32_bf16 v[24:27], v[148:151], v[214:217], v[24:27]
	v_mfma_f32_16x16x32_bf16 v[24:27], v[152:155], v[218:221], v[24:27]
	v_mfma_f32_16x16x32_bf16 v[8:11], v[152:155], v[226:229], v[8:11]
	v_mfma_f32_16x16x32_bf16 v[8:11], v[148:151], v[222:225], v[8:11]
	s_setprio 0
	s_setprio 3
	v_mfma_f32_16x16x32_bf16 v[52:55], v[172:175], v[198:201], v[52:55]
	v_mfma_f32_16x16x32_bf16 v[52:55], v[180:183], v[202:205], v[52:55]
	v_mfma_f32_16x16x32_bf16 v[36:39], v[180:183], v[210:213], v[36:39]
	v_mfma_f32_16x16x32_bf16 v[36:39], v[172:175], v[206:209], v[36:39]
	v_mfma_f32_16x16x32_bf16 v[20:23], v[172:175], v[214:217], v[20:23]
	v_mfma_f32_16x16x32_bf16 v[20:23], v[180:183], v[218:221], v[20:23]
	v_mfma_f32_16x16x32_bf16 v[4:7], v[180:183], v[226:229], v[4:7]
	v_mfma_f32_16x16x32_bf16 v[4:7], v[172:175], v[222:225], v[4:7]
	v_mfma_f32_16x16x32_bf16 v[44:47], v[184:187], v[198:201], v[44:47]
	v_mfma_f32_16x16x32_bf16 v[44:47], v[194:197], v[202:205], v[44:47]
	v_mfma_f32_16x16x32_bf16 v[28:31], v[194:197], v[210:213], v[28:31]
	v_mfma_f32_16x16x32_bf16 v[28:31], v[184:187], v[206:209], v[28:31]
	v_mfma_f32_16x16x32_bf16 v[12:15], v[184:187], v[214:217], v[12:15]
	v_mfma_f32_16x16x32_bf16 v[12:15], v[194:197], v[218:221], v[12:15]
	v_mfma_f32_16x16x32_bf16 v[0:3], v[194:197], v[226:229], v[0:3]
	v_mfma_f32_16x16x32_bf16 v[0:3], v[184:187], v[222:225], v[0:3]
	s_setprio 0
	s_barrier
; #define PG8_STAGE(bufoff, gbase, voff) do { _Pragma("unroll") for (int _i = 0; _i < 2; ++_i) \
;         __builtin_amdgcn_global_load_lds((const unsigned*)((const char*)(gbase) + (voff)[_i]), (LAS unsigned*)(lds + (bufoff) + ldsw + _i * 8192), 16, 0, 0); } while (0)
; #define PG8_LDA(dst, b, h) do { _Pragma("unroll") for (int m = 0; m < 4; ++m) _Pragma("unroll") for (int k = 0; k < 2; ++k) dst[m][k] = *(const LAS bf16x8*)(lds + PG8_SA(b, h) + aoff + m * 2048 + k * 1024); } while (0)
; #define PG8_LDB(dst, b, h) do { _Pragma("unroll") for (int n = 0; n < 2; ++n) _Pragma("unroll") for (int k = 0; k < 2; ++k) dst[n][k] = *(const LAS bf16x8*)(lds + PG8_SB(b, h) + boff + n * 2048 + k * 1024); } while (0)
; #define PG8_MMA(ai, bj, At, Bt) do { __builtin_amdgcn_s_setprio(3); _Pragma("unroll") for (int m = 0; m < 4; ++m) _Pragma("unroll") for (int n = 0; n < 2; ++n) _Pragma("unroll") for (int k = 0; k < 2; ++k) \
;         acc[ai][bj][m][n] = __builtin_amdgcn_mfma_f32_16x16x32_bf16(Bt[n][k], At[m][k], acc[ai][bj][m][n], 0, 0, 0); __builtin_amdgcn_s_setprio(0); } while (0)
; #define PG8_WAIT_V(n) asm volatile("s_waitcnt vmcnt(" #n ")" ::: "memory")
; #define PG8_WAIT_L(n) asm volatile("s_waitcnt lgkmcnt(" #n ")" ::: "memory")
; #define PG8_BAR __builtin_amdgcn_s_barrier()
; #define PG8_SCHED __builtin_amdgcn_sched_barrier(0)
; template <class Epi>
; __device__ __forceinline__ void gemm_phase(LAS unsigned char* lds, const Gemm g, const StaticOrder& S, const Epi& E, const int tid) {
;     ...
;             PG8_LDB(B0, 1, 0); PG8_LDB(B1, 1, 1); PG8_SCHED; PG8_LDA(At, 1, 0); PG8_STAGE(PG8_SA(0, 1), a2 + hstepA, voffA);
;             PG8_WAIT_V(8); PG8_WAIT_L(0); PG8_BAR; PG8_MMA(0, 0, At, B0); PG8_MMA(0, 1, At, B1); PG8_BAR; PG8_SCHED;
	s_add_i32 s21, 0, 0x18000
	s_add_i32 s55, 0, 0x1c000
	v_add_u32_e32 v152, s21, v169
	v_add_u32_e32 v176, s55, v169
	ds_read_b128 v[140:143], v152
	ds_read_b128 v[144:147], v152 offset:1024
	ds_read_b128 v[148:151], v152 offset:2048
	ds_read_b128 v[152:155], v152 offset:3072
	ds_read_b128 v[172:175], v176
	ds_read_b128 v[180:183], v176 offset:1024
	ds_read_b128 v[184:187], v176 offset:2048
	ds_read_b128 v[194:197], v176 offset:3072
	s_add_u32 s6, s6, s26
	s_addc_u32 s7, s7, 0
	s_mov_b32 m0, s96
	v_lshl_add_u64 v[252:253], s[6:7], 0, v[128:129]
	ds_read_b128 v[198:201], v171 offset:32768
	ds_read_b128 v[202:205], v171 offset:33792
	ds_read_b128 v[206:209], v171 offset:34816
	ds_read_b128 v[210:213], v171 offset:35840
	ds_read_b128 v[214:217], v171 offset:36864
	ds_read_b128 v[218:221], v171 offset:37888
	ds_read_b128 v[222:225], v171 offset:38912
	ds_read_b128 v[226:229], v171 offset:39936
	global_load_lds_dwordx4 v[252:253], off
	v_lshl_add_u64 v[252:253], s[6:7], 0, v[132:133]
	s_mov_b32 m0, s97
	s_nop 0
	global_load_lds_dwordx4 v[252:253], off
	s_waitcnt vmcnt(8)
	s_waitcnt lgkmcnt(0)
	s_barrier
	s_setprio 3
	s_waitcnt lgkmcnt(0)
	v_mfma_f32_16x16x32_bf16 v[124:127], v[140:143], v[198:201], v[124:127]
	v_mfma_f32_16x16x32_bf16 v[124:127], v[144:147], v[202:205], v[124:127]
	v_mfma_f32_16x16x32_bf16 v[116:119], v[144:147], v[210:213], v[116:119]
	v_mfma_f32_16x16x32_bf16 v[116:119], v[140:143], v[206:209], v[116:119]
	v_mfma_f32_16x16x32_bf16 v[100:103], v[140:143], v[214:217], v[100:103]
	v_mfma_f32_16x16x32_bf16 v[100:103], v[144:147], v[218:221], v[100:103]
	v_mfma_f32_16x16x32_bf16 v[84:87], v[144:147], v[226:229], v[84:87]
	v_mfma_f32_16x16x32_bf16 v[84:87], v[140:143], v[222:225], v[84:87]
	v_mfma_f32_16x16x32_bf16 v[120:123], v[148:151], v[198:201], v[120:123]
	v_mfma_f32_16x16x32_bf16 v[120:123], v[152:155], v[202:205], v[120:123]
	v_mfma_f32_16x16x32_bf16 v[108:111], v[152:155], v[210:213], v[108:111]
	v_mfma_f32_16x16x32_bf16 v[108:111], v[148:151], v[206:209], v[108:111]
	v_mfma_f32_16x16x32_bf16 v[92:95], v[148:151], v[214:217], v[92:95]
	v_mfma_f32_16x16x32_bf16 v[92:95], v[152:155], v[218:221], v[92:95]
	v_mfma_f32_16x16x32_bf16 v[76:79], v[152:155], v[226:229], v[76:79]
	v_mfma_f32_16x16x32_bf16 v[76:79], v[148:151], v[222:225], v[76:79]
	s_setprio 0
	s_setprio 3
	v_mfma_f32_16x16x32_bf16 v[112:115], v[172:175], v[198:201], v[112:115]
	v_mfma_f32_16x16x32_bf16 v[112:115], v[180:183], v[202:205], v[112:115]
	v_mfma_f32_16x16x32_bf16 v[96:99], v[180:183], v[210:213], v[96:99]
	v_mfma_f32_16x16x32_bf16 v[96:99], v[172:175], v[206:209], v[96:99]
	v_mfma_f32_16x16x32_bf16 v[80:83], v[172:175], v[214:217], v[80:83]
	v_mfma_f32_16x16x32_bf16 v[80:83], v[180:183], v[218:221], v[80:83]
	v_mfma_f32_16x16x32_bf16 v[68:71], v[180:183], v[226:229], v[68:71]
	v_mfma_f32_16x16x32_bf16 v[68:71], v[172:175], v[222:225], v[68:71]
	v_mfma_f32_16x16x32_bf16 v[104:107], v[184:187], v[198:201], v[104:107]
	v_mfma_f32_16x16x32_bf16 v[104:107], v[194:197], v[202:205], v[104:107]
	v_mfma_f32_16x16x32_bf16 v[88:91], v[194:197], v[210:213], v[88:91]
	v_mfma_f32_16x16x32_bf16 v[88:91], v[184:187], v[206:209], v[88:91]
	v_mfma_f32_16x16x32_bf16 v[72:75], v[184:187], v[214:217], v[72:75]
	v_mfma_f32_16x16x32_bf16 v[72:75], v[194:197], v[218:221], v[72:75]
	v_mfma_f32_16x16x32_bf16 v[64:67], v[194:197], v[226:229], v[64:67]
	v_mfma_f32_16x16x32_bf16 v[64:67], v[184:187], v[222:225], v[64:67]
	s_setprio 0
	s_barrier
; #define PG8_STAGE(bufoff, gbase, voff) do { _Pragma("unroll") for (int _i = 0; _i < 2; ++_i) \
;         __builtin_amdgcn_global_load_lds((const unsigned*)((const char*)(gbase) + (voff)[_i]), (LAS unsigned*)(lds + (bufoff) + ldsw + _i * 8192), 16, 0, 0); } while (0)
; #define PG8_LDA(dst, b, h) do { _Pragma("unroll") for (int m = 0; m < 4; ++m) _Pragma("unroll") for (int k = 0; k < 2; ++k) dst[m][k] = *(const LAS bf16x8*)(lds + PG8_SA(b, h) + aoff + m * 2048 + k * 1024); } while (0)
; #define PG8_MMA(ai, bj, At, Bt) do { __builtin_amdgcn_s_setprio(3); _Pragma("unroll") for (int m = 0; m < 4; ++m) _Pragma("unroll") for (int n = 0; n < 2; ++n) _Pragma("unroll") for (int k = 0; k < 2; ++k) \
;         acc[ai][bj][m][n] = __builtin_amdgcn_mfma_f32_16x16x32_bf16(Bt[n][k], At[m][k], acc[ai][bj][m][n], 0, 0, 0); __builtin_amdgcn_s_setprio(0); } while (0)
; #define PG8_WAIT_V(n) asm volatile("s_waitcnt vmcnt(" #n ")" ::: "memory")
; #define PG8_WAIT_L(n) asm volatile("s_waitcnt lgkmcnt(" #n ")" ::: "memory")
; #define PG8_BAR __builtin_amdgcn_s_barrier()
; #define PG8_SCHED __builtin_amdgcn_sched_barrier(0)
; template <class Epi>
; __device__ __forceinline__ void gemm_phase(LAS unsigned char* lds, const Gemm g, const StaticOrder& S, const Epi& E, const int tid) {
;     ...
;         for (int t = 0; t < nt; t += 2) {
;     ...
;             PG8_LDA(At, 1, 1); PG8_STAGE(PG8_SB(1, 0), b3, voffB); PG8_STAGE(PG8_SB(1, 1), b3 + hstepB, voffB); PG8_STAGE(PG8_SA(1, 0), a3, voffA);
;             PG8_WAIT_V(8); PG8_WAIT_L(0); PG8_BAR; PG8_MMA(1, 0, At, B0); PG8_MMA(1, 1, At, B1); PG8_BAR; PG8_SCHED;
	s_add_i32 s6, s21, s93
	v_lshl_add_u64 v[156:157], v[156:157], 0, s[22:23]
	s_mov_b32 m0, s6
	ds_read_b128 v[198:201], v171 offset:49152
	ds_read_b128 v[202:205], v171 offset:50176
	ds_read_b128 v[206:209], v171 offset:51200
	ds_read_b128 v[210:213], v171 offset:52224
	ds_read_b128 v[214:217], v171 offset:53248
	ds_read_b128 v[218:221], v171 offset:54272
	ds_read_b128 v[222:225], v171 offset:55296
	ds_read_b128 v[226:229], v171 offset:56320
	global_load_lds_dwordx4 v[156:157], off
	v_lshl_add_u64 v[156:157], v[190:191], 0, s[22:23]
	s_add_i32 m0, s6, 0x2000
	s_add_i32 s6, s55, s93
	global_load_lds_dwordx4 v[156:157], off
	v_lshl_add_u64 v[156:157], v[240:241], 0, s[22:23]
	s_mov_b32 m0, s6
	s_nop 0
	global_load_lds_dwordx4 v[156:157], off
	v_lshl_add_u64 v[156:157], v[242:243], 0, s[22:23]
	s_add_i32 m0, s6, 0x2000
	s_nop 0
	global_load_lds_dwordx4 v[156:157], off
	v_lshl_add_u64 v[156:157], v[244:245], 0, s[22:23]
	s_mov_b32 m0, s98
	s_nop 0
	global_load_lds_dwordx4 v[156:157], off
	v_lshl_add_u64 v[156:157], v[246:247], 0, s[22:23]
	s_mov_b32 m0, s99
	s_nop 0
	global_load_lds_dwordx4 v[156:157], off
	s_waitcnt vmcnt(8)
	s_waitcnt lgkmcnt(0)
	s_barrier
	s_setprio 3
	s_waitcnt lgkmcnt(0)
	v_mfma_f32_16x16x32_bf16 v[60:63], v[140:143], v[198:201], v[60:63]
	v_mfma_f32_16x16x32_bf16 v[60:63], v[144:147], v[202:205], v[60:63]
	v_mfma_f32_16x16x32_bf16 v[48:51], v[144:147], v[210:213], v[48:51]
	v_mfma_f32_16x16x32_bf16 v[48:51], v[140:143], v[206:209], v[48:51]
	v_mfma_f32_16x16x32_bf16 v[32:35], v[140:143], v[214:217], v[32:35]
	v_mfma_f32_16x16x32_bf16 v[32:35], v[144:147], v[218:221], v[32:35]
	v_mfma_f32_16x16x32_bf16 v[16:19], v[144:147], v[226:229], v[16:19]
	v_mfma_f32_16x16x32_bf16 v[16:19], v[140:143], v[222:225], v[16:19]
	v_mfma_f32_16x16x32_bf16 v[56:59], v[148:151], v[198:201], v[56:59]
	v_mfma_f32_16x16x32_bf16 v[56:59], v[152:155], v[202:205], v[56:59]
	v_mfma_f32_16x16x32_bf16 v[40:43], v[152:155], v[210:213], v[40:43]
	v_mfma_f32_16x16x32_bf16 v[40:43], v[148:151], v[206:209], v[40:43]
	v_mfma_f32_16x16x32_bf16 v[24:27], v[148:151], v[214:217], v[24:27]
	v_mfma_f32_16x16x32_bf16 v[24:27], v[152:155], v[218:221], v[24:27]
	v_mfma_f32_16x16x32_bf16 v[8:11], v[152:155], v[226:229], v[8:11]
	v_mfma_f32_16x16x32_bf16 v[8:11], v[148:151], v[222:225], v[8:11]
	s_setprio 0
	s_setprio 3
	v_mfma_f32_16x16x32_bf16 v[52:55], v[172:175], v[198:201], v[52:55]
	v_mfma_f32_16x16x32_bf16 v[52:55], v[180:183], v[202:205], v[52:55]
	v_mfma_f32_16x16x32_bf16 v[36:39], v[180:183], v[210:213], v[36:39]
	v_mfma_f32_16x16x32_bf16 v[36:39], v[172:175], v[206:209], v[36:39]
	v_mfma_f32_16x16x32_bf16 v[20:23], v[172:175], v[214:217], v[20:23]
	v_mfma_f32_16x16x32_bf16 v[20:23], v[180:183], v[218:221], v[20:23]
	v_mfma_f32_16x16x32_bf16 v[4:7], v[180:183], v[226:229], v[4:7]
	v_mfma_f32_16x16x32_bf16 v[4:7], v[172:175], v[222:225], v[4:7]
	v_mfma_f32_16x16x32_bf16 v[44:47], v[184:187], v[198:201], v[44:47]
	v_mfma_f32_16x16x32_bf16 v[44:47], v[194:197], v[202:205], v[44:47]
	v_mfma_f32_16x16x32_bf16 v[28:31], v[194:197], v[210:213], v[28:31]
	v_mfma_f32_16x16x32_bf16 v[28:31], v[184:187], v[206:209], v[28:31]
	v_mfma_f32_16x16x32_bf16 v[12:15], v[184:187], v[214:217], v[12:15]
	v_mfma_f32_16x16x32_bf16 v[12:15], v[194:197], v[218:221], v[12:15]
	v_mfma_f32_16x16x32_bf16 v[0:3], v[194:197], v[226:229], v[0:3]
	v_mfma_f32_16x16x32_bf16 v[0:3], v[184:187], v[222:225], v[0:3]
	s_setprio 0
	s_barrier
	s_add_u32 s30, s30, 0x100
	s_addc_u32 s31, s31, 0
	s_add_u32 s4, s4, 0x100
	s_addc_u32 s5, s5, 0
	s_cmp_ge_u32 s20, s89
	s_mov_b32 s6, s20
	s_cbranch_scc0 .LBB0_265
